# GEMM K-loop: per-phase counted LDS-DMA waits vmcnt(10) one phase before first read instead of vmcnt(6) at phases 4 and 8
# baseline (speedup 1.0000x reference)
.LBB0_141:
	s_add_i32 s72, s40, 2
	s_add_u32 s68, s0, 0x80
	s_addc_u32 s41, s1, 0
	s_add_i32 s73, 0, 0x10000
	v_add_u32_e32 v140, s73, v183
	ds_read_b128 v[128:131], v140
	ds_read_b128 v[132:135], v140 offset:1024
	ds_read_b128 v[136:139], v140 offset:2048
	ds_read_b128 v[140:143], v140 offset:3072
	s_cmp_eq_u32 s10, s40
	s_cselect_b32 s40, s64, s68
	s_cselect_b32 s41, s65, s41
	s_cselect_b32 s69, s67, s71
	s_cselect_b32 s68, s66, s70
	v_lshl_add_u64 v[176:177], s[0:1], 0, v[192:193]
	s_add_i32 m0, s76, 0xc000
	ds_read_b128 v[144:147], v239
	ds_read_b128 v[148:151], v239 offset:1024
	ds_read_b128 v[152:155], v239 offset:2048
	ds_read_b128 v[156:159], v239 offset:3072
	ds_read_b128 v[160:163], v239 offset:4096
	ds_read_b128 v[164:167], v239 offset:5120
	ds_read_b128 v[168:171], v239 offset:6144
	ds_read_b128 v[172:175], v239 offset:7168
	global_load_lds_dwordx4 v[176:177], off
	v_lshl_add_u64 v[176:177], s[0:1], 0, v[194:195]
	s_add_i32 m0, s76, 0xe000
	s_nop 0
	global_load_lds_dwordx4 v[176:177], off
	s_waitcnt lgkmcnt(8)
	s_waitcnt vmcnt(10)
	s_barrier
	s_waitcnt lgkmcnt(0)
	s_setprio 1
	s_waitcnt lgkmcnt(0)
	v_mfma_f32_16x16x32_bf16 v[124:127], v[128:131], v[144:147], v[124:127]
	v_mfma_f32_16x16x32_bf16 v[116:119], v[136:139], v[144:147], v[116:119]
	v_mfma_f32_16x16x32_bf16 v[108:111], v[128:131], v[152:155], v[108:111]
	v_mfma_f32_16x16x32_bf16 v[100:103], v[136:139], v[152:155], v[100:103]
	v_mfma_f32_16x16x32_bf16 v[92:95], v[128:131], v[160:163], v[92:95]
	v_mfma_f32_16x16x32_bf16 v[84:87], v[136:139], v[160:163], v[84:87]
	v_mfma_f32_16x16x32_bf16 v[76:79], v[128:131], v[168:171], v[76:79]
	v_mfma_f32_16x16x32_bf16 v[68:71], v[136:139], v[168:171], v[68:71]
	v_mfma_f32_16x16x32_bf16 v[124:127], v[132:135], v[148:151], v[124:127]
	v_mfma_f32_16x16x32_bf16 v[116:119], v[140:143], v[148:151], v[116:119]
	v_mfma_f32_16x16x32_bf16 v[108:111], v[132:135], v[156:159], v[108:111]
	v_mfma_f32_16x16x32_bf16 v[100:103], v[140:143], v[156:159], v[100:103]
	v_mfma_f32_16x16x32_bf16 v[92:95], v[132:135], v[164:167], v[92:95]
	v_mfma_f32_16x16x32_bf16 v[84:87], v[140:143], v[164:167], v[84:87]
	v_mfma_f32_16x16x32_bf16 v[76:79], v[132:135], v[172:175], v[76:79]
	v_mfma_f32_16x16x32_bf16 v[68:71], v[140:143], v[172:175], v[68:71]
	s_setprio 0
	s_barrier
	s_add_i32 s80, 0, 0x14000
	s_add_i32 s73, s73, s33
	v_add_u32_e32 v204, s80, v183
	v_lshl_add_u64 v[208:209], s[68:69], 0, v[186:187]
	s_mov_b32 m0, s73
	ds_read_b128 v[176:179], v204
	ds_read_b128 v[196:199], v204 offset:1024
	ds_read_b128 v[200:203], v204 offset:2048
	ds_read_b128 v[204:207], v204 offset:3072
	global_load_lds_dwordx4 v[208:209], off
	v_lshl_add_u64 v[210:211], s[68:69], 0, v[190:191]
	s_add_i32 m0, s73, 0x2000
	s_nop 0
	global_load_lds_dwordx4 v[210:211], off
	s_waitcnt vmcnt(10)
	s_barrier
	s_waitcnt lgkmcnt(0)
	s_setprio 1
	s_waitcnt lgkmcnt(0)
	v_mfma_f32_16x16x32_bf16 v[120:123], v[176:179], v[144:147], v[120:123]
	v_mfma_f32_16x16x32_bf16 v[112:115], v[200:203], v[144:147], v[112:115]
	v_mfma_f32_16x16x32_bf16 v[104:107], v[176:179], v[152:155], v[104:107]
	v_mfma_f32_16x16x32_bf16 v[96:99], v[200:203], v[152:155], v[96:99]
	v_mfma_f32_16x16x32_bf16 v[88:91], v[176:179], v[160:163], v[88:91]
	v_mfma_f32_16x16x32_bf16 v[80:83], v[200:203], v[160:163], v[80:83]
	v_mfma_f32_16x16x32_bf16 v[72:75], v[176:179], v[168:171], v[72:75]
	v_mfma_f32_16x16x32_bf16 v[64:67], v[200:203], v[168:171], v[64:67]
	v_mfma_f32_16x16x32_bf16 v[120:123], v[196:199], v[148:151], v[120:123]
	v_mfma_f32_16x16x32_bf16 v[112:115], v[204:207], v[148:151], v[112:115]
	v_mfma_f32_16x16x32_bf16 v[104:107], v[196:199], v[156:159], v[104:107]
	v_mfma_f32_16x16x32_bf16 v[96:99], v[204:207], v[156:159], v[96:99]
	v_mfma_f32_16x16x32_bf16 v[88:91], v[196:199], v[164:167], v[88:91]
	v_mfma_f32_16x16x32_bf16 v[80:83], v[204:207], v[164:167], v[80:83]
	v_mfma_f32_16x16x32_bf16 v[72:75], v[196:199], v[172:175], v[72:75]
	v_mfma_f32_16x16x32_bf16 v[64:67], v[204:207], v[172:175], v[64:67]
	s_setprio 0
	s_mov_b32 m0, s76
	v_lshl_add_u64 v[212:213], s[40:41], 0, v[184:185]
	s_barrier
	ds_read_b128 v[144:147], v239 offset:16384
	ds_read_b128 v[148:151], v239 offset:17408
	ds_read_b128 v[152:155], v239 offset:18432
	ds_read_b128 v[156:159], v239 offset:19456
	ds_read_b128 v[160:163], v239 offset:20480
	ds_read_b128 v[164:167], v239 offset:21504
	ds_read_b128 v[168:171], v239 offset:22528
	ds_read_b128 v[172:175], v239 offset:23552
	global_load_lds_dwordx4 v[212:213], off
	v_lshl_add_u64 v[214:215], s[40:41], 0, v[188:189]
	s_mov_b32 m0, s4
	s_nop 0
	global_load_lds_dwordx4 v[214:215], off
	s_barrier
	s_waitcnt lgkmcnt(0)
	s_setprio 1
	s_waitcnt lgkmcnt(0)
	v_mfma_f32_16x16x32_bf16 v[60:63], v[128:131], v[144:147], v[60:63]
	v_mfma_f32_16x16x32_bf16 v[52:55], v[136:139], v[144:147], v[52:55]
	v_mfma_f32_16x16x32_bf16 v[44:47], v[128:131], v[152:155], v[44:47]
	v_mfma_f32_16x16x32_bf16 v[36:39], v[136:139], v[152:155], v[36:39]
	v_mfma_f32_16x16x32_bf16 v[28:31], v[128:131], v[160:163], v[28:31]
	v_mfma_f32_16x16x32_bf16 v[20:23], v[136:139], v[160:163], v[20:23]
	v_mfma_f32_16x16x32_bf16 v[12:15], v[128:131], v[168:171], v[12:15]
	v_mfma_f32_16x16x32_bf16 v[4:7], v[136:139], v[168:171], v[4:7]
	v_mfma_f32_16x16x32_bf16 v[60:63], v[132:135], v[148:151], v[60:63]
	v_mfma_f32_16x16x32_bf16 v[52:55], v[140:143], v[148:151], v[52:55]
	v_mfma_f32_16x16x32_bf16 v[44:47], v[132:135], v[156:159], v[44:47]
	v_mfma_f32_16x16x32_bf16 v[36:39], v[140:143], v[156:159], v[36:39]
	v_mfma_f32_16x16x32_bf16 v[28:31], v[132:135], v[164:167], v[28:31]
	v_mfma_f32_16x16x32_bf16 v[20:23], v[140:143], v[164:167], v[20:23]
	v_mfma_f32_16x16x32_bf16 v[12:15], v[132:135], v[172:175], v[12:15]
	v_mfma_f32_16x16x32_bf16 v[4:7], v[140:143], v[172:175], v[4:7]
	s_setprio 0
	s_barrier
	s_add_u32 s68, s68, s98
	s_addc_u32 s69, s69, 0
	s_add_i32 s73, s80, s33
	v_lshl_add_u64 v[216:217], s[68:69], 0, v[186:187]
	s_mov_b32 m0, s73
	v_lshl_add_u64 v[218:219], s[68:69], 0, v[190:191]
	global_load_lds_dwordx4 v[216:217], off
	s_add_i32 m0, s73, 0x2000
	s_nop 0
	global_load_lds_dwordx4 v[218:219], off
	s_waitcnt vmcnt(10)
	s_barrier
	s_setprio 1
	v_mfma_f32_16x16x32_bf16 v[56:59], v[176:179], v[144:147], v[56:59]
	v_mfma_f32_16x16x32_bf16 v[48:51], v[200:203], v[144:147], v[48:51]
	v_mfma_f32_16x16x32_bf16 v[40:43], v[176:179], v[152:155], v[40:43]
	v_mfma_f32_16x16x32_bf16 v[32:35], v[200:203], v[152:155], v[32:35]
	v_mfma_f32_16x16x32_bf16 v[24:27], v[176:179], v[160:163], v[24:27]
	v_mfma_f32_16x16x32_bf16 v[16:19], v[200:203], v[160:163], v[16:19]
	v_mfma_f32_16x16x32_bf16 v[8:11], v[176:179], v[168:171], v[8:11]
	v_mfma_f32_16x16x32_bf16 v[0:3], v[200:203], v[168:171], v[0:3]
	v_mfma_f32_16x16x32_bf16 v[56:59], v[196:199], v[148:151], v[56:59]
	v_mfma_f32_16x16x32_bf16 v[48:51], v[204:207], v[148:151], v[48:51]
	v_mfma_f32_16x16x32_bf16 v[40:43], v[196:199], v[156:159], v[40:43]
	v_mfma_f32_16x16x32_bf16 v[32:35], v[204:207], v[156:159], v[32:35]
	v_mfma_f32_16x16x32_bf16 v[24:27], v[196:199], v[164:167], v[24:27]
	v_mfma_f32_16x16x32_bf16 v[16:19], v[204:207], v[164:167], v[16:19]
	v_mfma_f32_16x16x32_bf16 v[8:11], v[196:199], v[172:175], v[8:11]
	v_mfma_f32_16x16x32_bf16 v[0:3], v[204:207], v[172:175], v[0:3]
	s_setprio 0
	s_add_i32 s68, 0, 0x18000
	v_add_u32_e32 v140, s68, v183
	s_barrier
	ds_read_b128 v[128:131], v140
	ds_read_b128 v[132:135], v140 offset:1024
	ds_read_b128 v[136:139], v140 offset:2048
	ds_read_b128 v[140:143], v140 offset:3072
	s_add_u32 s40, s40, s98
	s_addc_u32 s41, s41, 0
	s_mov_b32 m0, s5
	v_lshl_add_u64 v[176:177], s[40:41], 0, v[184:185]
	ds_read_b128 v[144:147], v239 offset:32768
	ds_read_b128 v[148:151], v239 offset:33792
	ds_read_b128 v[152:155], v239 offset:34816
	ds_read_b128 v[156:159], v239 offset:35840
	ds_read_b128 v[160:163], v239 offset:36864
	ds_read_b128 v[164:167], v239 offset:37888
	ds_read_b128 v[168:171], v239 offset:38912
	ds_read_b128 v[172:175], v239 offset:39936
	global_load_lds_dwordx4 v[176:177], off
	v_lshl_add_u64 v[176:177], s[40:41], 0, v[188:189]
	s_mov_b32 m0, s6
	s_nop 0
	global_load_lds_dwordx4 v[176:177], off
	s_waitcnt lgkmcnt(8)
	s_waitcnt vmcnt(10)
	s_barrier
	s_waitcnt lgkmcnt(0)
	s_setprio 1
	s_waitcnt lgkmcnt(0)
	v_mfma_f32_16x16x32_bf16 v[124:127], v[128:131], v[144:147], v[124:127]
	v_mfma_f32_16x16x32_bf16 v[116:119], v[136:139], v[144:147], v[116:119]
	v_mfma_f32_16x16x32_bf16 v[108:111], v[128:131], v[152:155], v[108:111]
	v_mfma_f32_16x16x32_bf16 v[100:103], v[136:139], v[152:155], v[100:103]
	v_mfma_f32_16x16x32_bf16 v[92:95], v[128:131], v[160:163], v[92:95]
	v_mfma_f32_16x16x32_bf16 v[84:87], v[136:139], v[160:163], v[84:87]
	v_mfma_f32_16x16x32_bf16 v[76:79], v[128:131], v[168:171], v[76:79]
	v_mfma_f32_16x16x32_bf16 v[68:71], v[136:139], v[168:171], v[68:71]
	v_mfma_f32_16x16x32_bf16 v[124:127], v[132:135], v[148:151], v[124:127]
	v_mfma_f32_16x16x32_bf16 v[116:119], v[140:143], v[148:151], v[116:119]
	v_mfma_f32_16x16x32_bf16 v[108:111], v[132:135], v[156:159], v[108:111]
	v_mfma_f32_16x16x32_bf16 v[100:103], v[140:143], v[156:159], v[100:103]
	v_mfma_f32_16x16x32_bf16 v[92:95], v[132:135], v[164:167], v[92:95]
	v_mfma_f32_16x16x32_bf16 v[84:87], v[140:143], v[164:167], v[84:87]
	v_mfma_f32_16x16x32_bf16 v[76:79], v[132:135], v[172:175], v[76:79]
	v_mfma_f32_16x16x32_bf16 v[68:71], v[140:143], v[172:175], v[68:71]
	s_setprio 0
	s_barrier
	s_add_i32 s40, 0, 0x1c000
	s_add_i32 s41, s68, s33
	v_add_u32_e32 v204, s40, v183
	v_lshl_add_u64 v[208:209], v[208:209], 0, s[96:97]
	s_mov_b32 m0, s41
	ds_read_b128 v[176:179], v204
	ds_read_b128 v[196:199], v204 offset:1024
	ds_read_b128 v[200:203], v204 offset:2048
	ds_read_b128 v[204:207], v204 offset:3072
	global_load_lds_dwordx4 v[208:209], off
	v_lshl_add_u64 v[208:209], v[210:211], 0, s[96:97]
	s_add_i32 m0, s41, 0x2000
	s_nop 0
	global_load_lds_dwordx4 v[208:209], off
	s_waitcnt vmcnt(10)
	s_barrier
	s_waitcnt lgkmcnt(0)
	s_setprio 1
	s_waitcnt lgkmcnt(0)
	v_mfma_f32_16x16x32_bf16 v[120:123], v[176:179], v[144:147], v[120:123]
	v_mfma_f32_16x16x32_bf16 v[112:115], v[200:203], v[144:147], v[112:115]
	v_mfma_f32_16x16x32_bf16 v[104:107], v[176:179], v[152:155], v[104:107]
	v_mfma_f32_16x16x32_bf16 v[96:99], v[200:203], v[152:155], v[96:99]
	v_mfma_f32_16x16x32_bf16 v[88:91], v[176:179], v[160:163], v[88:91]
	v_mfma_f32_16x16x32_bf16 v[80:83], v[200:203], v[160:163], v[80:83]
	v_mfma_f32_16x16x32_bf16 v[72:75], v[176:179], v[168:171], v[72:75]
	v_mfma_f32_16x16x32_bf16 v[64:67], v[200:203], v[168:171], v[64:67]
	v_mfma_f32_16x16x32_bf16 v[120:123], v[196:199], v[148:151], v[120:123]
	v_mfma_f32_16x16x32_bf16 v[112:115], v[204:207], v[148:151], v[112:115]
	v_mfma_f32_16x16x32_bf16 v[104:107], v[196:199], v[156:159], v[104:107]
	v_mfma_f32_16x16x32_bf16 v[96:99], v[204:207], v[156:159], v[96:99]
	v_mfma_f32_16x16x32_bf16 v[88:91], v[196:199], v[164:167], v[88:91]
	v_mfma_f32_16x16x32_bf16 v[80:83], v[204:207], v[164:167], v[80:83]
	v_mfma_f32_16x16x32_bf16 v[72:75], v[196:199], v[172:175], v[72:75]
	v_mfma_f32_16x16x32_bf16 v[64:67], v[204:207], v[172:175], v[64:67]
	s_setprio 0
	s_mov_b32 m0, s8
	v_lshl_add_u64 v[208:209], v[212:213], 0, s[96:97]
	s_barrier
	ds_read_b128 v[144:147], v239 offset:49152
	ds_read_b128 v[148:151], v239 offset:50176
	ds_read_b128 v[152:155], v239 offset:51200
	ds_read_b128 v[156:159], v239 offset:52224
	ds_read_b128 v[160:163], v239 offset:53248
	ds_read_b128 v[164:167], v239 offset:54272
	ds_read_b128 v[168:171], v239 offset:55296
	ds_read_b128 v[172:175], v239 offset:56320
	global_load_lds_dwordx4 v[208:209], off
	v_lshl_add_u64 v[208:209], v[214:215], 0, s[96:97]
	s_mov_b32 m0, s9
	s_nop 0
	global_load_lds_dwordx4 v[208:209], off
	s_barrier
	s_waitcnt lgkmcnt(0)
	s_setprio 1
	s_waitcnt lgkmcnt(0)
	v_mfma_f32_16x16x32_bf16 v[60:63], v[128:131], v[144:147], v[60:63]
	v_mfma_f32_16x16x32_bf16 v[52:55], v[136:139], v[144:147], v[52:55]
	v_mfma_f32_16x16x32_bf16 v[44:47], v[128:131], v[152:155], v[44:47]
	v_mfma_f32_16x16x32_bf16 v[36:39], v[136:139], v[152:155], v[36:39]
	v_mfma_f32_16x16x32_bf16 v[28:31], v[128:131], v[160:163], v[28:31]
	v_mfma_f32_16x16x32_bf16 v[20:23], v[136:139], v[160:163], v[20:23]
	v_mfma_f32_16x16x32_bf16 v[12:15], v[128:131], v[168:171], v[12:15]
	v_mfma_f32_16x16x32_bf16 v[4:7], v[136:139], v[168:171], v[4:7]
	v_mfma_f32_16x16x32_bf16 v[60:63], v[132:135], v[148:151], v[60:63]
	v_mfma_f32_16x16x32_bf16 v[52:55], v[140:143], v[148:151], v[52:55]
	v_mfma_f32_16x16x32_bf16 v[44:47], v[132:135], v[156:159], v[44:47]
	v_mfma_f32_16x16x32_bf16 v[36:39], v[140:143], v[156:159], v[36:39]
	v_mfma_f32_16x16x32_bf16 v[28:31], v[132:135], v[164:167], v[28:31]
	v_mfma_f32_16x16x32_bf16 v[20:23], v[140:143], v[164:167], v[20:23]
	v_mfma_f32_16x16x32_bf16 v[12:15], v[132:135], v[172:175], v[12:15]
	v_mfma_f32_16x16x32_bf16 v[4:7], v[140:143], v[172:175], v[4:7]
	s_setprio 0
	s_barrier
	s_add_i32 s40, s40, s33
	v_lshl_add_u64 v[128:129], v[216:217], 0, s[96:97]
	s_mov_b32 m0, s40
	s_nop 0
	global_load_lds_dwordx4 v[128:129], off
	v_lshl_add_u64 v[128:129], v[218:219], 0, s[96:97]
	s_add_i32 m0, s40, 0x2000
	s_nop 0
	global_load_lds_dwordx4 v[128:129], off
	s_waitcnt vmcnt(10)
	s_barrier
	s_setprio 1
	v_mfma_f32_16x16x32_bf16 v[56:59], v[176:179], v[144:147], v[56:59]
	v_mfma_f32_16x16x32_bf16 v[48:51], v[200:203], v[144:147], v[48:51]
	v_mfma_f32_16x16x32_bf16 v[40:43], v[176:179], v[152:155], v[40:43]
	v_mfma_f32_16x16x32_bf16 v[32:35], v[200:203], v[152:155], v[32:35]
	v_mfma_f32_16x16x32_bf16 v[24:27], v[176:179], v[160:163], v[24:27]
	v_mfma_f32_16x16x32_bf16 v[16:19], v[200:203], v[160:163], v[16:19]
	v_mfma_f32_16x16x32_bf16 v[8:11], v[176:179], v[168:171], v[8:11]
	v_mfma_f32_16x16x32_bf16 v[0:3], v[200:203], v[168:171], v[0:3]
	v_mfma_f32_16x16x32_bf16 v[56:59], v[196:199], v[148:151], v[56:59]
	v_mfma_f32_16x16x32_bf16 v[48:51], v[204:207], v[148:151], v[48:51]
	v_mfma_f32_16x16x32_bf16 v[40:43], v[196:199], v[156:159], v[40:43]
	v_mfma_f32_16x16x32_bf16 v[32:35], v[204:207], v[156:159], v[32:35]
	v_mfma_f32_16x16x32_bf16 v[24:27], v[196:199], v[164:167], v[24:27]
	v_mfma_f32_16x16x32_bf16 v[16:19], v[204:207], v[164:167], v[16:19]
	v_mfma_f32_16x16x32_bf16 v[8:11], v[196:199], v[172:175], v[8:11]
	v_mfma_f32_16x16x32_bf16 v[0:3], v[204:207], v[172:175], v[0:3]
	s_setprio 0
	s_add_u32 s0, s0, 0x100
	s_addc_u32 s1, s1, 0
	s_add_u32 s70, s70, 0x100
	s_addc_u32 s71, s71, 0
	s_cmp_ge_u32 s72, s7
	s_mov_b32 s40, s72
	s_barrier
	s_cbranch_scc0 .LBB0_141
	v_lshl_add_u32 v196, s19, 8, v181
	s_cmp_lt_i32 s78, 2
	s_mov_b64 s[0:1], -1
	s_cbranch_scc1 .LBB0_223
	s_cmp_gt_i32 s78, 2
	s_cbranch_scc0 .LBB0_220
	s_lshl_b32 s0, s18, 8
	s_ashr_i32 s68, s18, 1
	s_and_b32 s0, s0, 0x100
	s_cmp_lt_i32 s68, 2
	v_or_b32_e32 v148, s0, v238
	s_cselect_b64 s[0:1], -1, 0
	s_lshl_b32 s40, s68, 9
	s_add_i32 s80, s40, 0xfffffc00
	v_readlane_b32 s48, v241, 0
	s_lshl_b64 s[70:71], s[80:81], 2
	v_readlane_b32 s62, v241, 14
	v_readlane_b32 s63, v241, 15
	s_add_u32 s69, s62, s70
	s_addc_u32 s80, s63, s71
	s_ashr_i32 s41, s40, 31
	v_readlane_b32 s58, v241, 10
	s_lshl_b64 s[40:41], s[40:41], 2
	v_readlane_b32 s59, v241, 11
	s_add_u32 s99, s58, s40
	s_mov_b32 s83, s82
	s_addc_u32 s82, s59, s41
	s_cmp_lt_i32 s68, 4
	s_cselect_b64 s[72:73], -1, 0
	s_cmp_gt_i32 s68, 3
	s_cselect_b64 s[70:71], -1, 0
	v_mov_b32_e32 v132, 0
	s_and_b64 vcc, exec, s[70:71]
	v_lshlrev_b32_e32 v136, 2, v148
	v_mov_b32_e32 v140, 0
	v_mov_b32_e32 v141, v132
	v_mov_b32_e32 v142, 0
	v_mov_b32_e32 v143, 0
	v_readlane_b32 s49, v241, 1
	v_readlane_b32 s50, v241, 2
	v_readlane_b32 s51, v241, 3
	v_readlane_b32 s52, v241, 4
	v_readlane_b32 s53, v241, 5
	v_readlane_b32 s54, v241, 6
	v_readlane_b32 s55, v241, 7
	v_readlane_b32 s56, v241, 8
	v_readlane_b32 s57, v241, 9
	v_readlane_b32 s60, v241, 12
	v_readlane_b32 s61, v241, 13
	s_cbranch_vccnz .LBB0_146
	s_and_b64 s[40:41], s[0:1], exec
	s_cselect_b32 s41, s82, s80
	s_cselect_b32 s40, s99, s69
	global_load_dwordx4 v[140:143], v136, s[40:41]
